# seam 0: cooperative-groups grid.sync replaced by one-shot counter barrier (same fences)
# speedup vs baseline: 1.0088x; 1.0088x over previous
; #define SEAM(k) do { if (IN(k) && IN((k) + 1)) { if ((k) == 0) cg::this_grid().sync(); else xcd_barrier(xbar); } } while (0)
; #define REP(k) for (int rep_ = 0; rep_ < ((((REPMASK) >> (k)) & 1) ? 2 : 1); ++rep_, (((REPMASK) >> (k)) & 1) ? cg::this_grid().sync() : (void)0)
; __global__ void __launch_bounds__(512, 2) fwd_megakernel(Args a) {
;     ...
;     if (lo == 0 && hi == NPHASE) { for (int q_ = 0; q_ < SYNC_PROBE; ++q_) cg::this_grid().sync(); }
;     ...
;     if (IN(0)) REP(0) { if (rep_ == 0 && (REPMASK & 1)) phase0<P0_PROBE>(L, a); else phase0<15>(L, a); } SEAM(0);
.LBB0_109:
	s_cmp_gt_i32 s31, 1
	s_cselect_b64 s[0:1], -1, 0
	s_and_b64 s[4:5], s[64:65], s[0:1]
	s_andn2_b64 vcc, exec, s[4:5]
	s_cbranch_vccnz .LBB0_121
	v_cmp_eq_u32_e32 vcc, 0, v152
	s_waitcnt vmcnt(0) lgkmcnt(0)
	s_barrier
	s_and_saveexec_b64 s[4:5], vcc
	s_cbranch_execz .Lg0_done
	buffer_wbl2 sc1
	s_waitcnt vmcnt(0)
	v_mov_b32_e32 v1, 0x3800
	v_mov_b32_e32 v2, 1
	global_atomic_add v1, v2, s[66:67]
.Lg0_spin:
	global_load_dword v3, v1, s[66:67] sc1
	s_waitcnt vmcnt(0)
	v_cmp_gt_u32_e32 vcc, s3, v3
	s_cbranch_vccz .Lg0_acq
	s_sleep 1
	s_branch .Lg0_spin
.Lg0_acq:
	buffer_inv sc1
	s_waitcnt vmcnt(0)
